# kc item pp-loop: Ws table stored as (re,re,im,im) pairs in LDS so the 24 v_mov shuffles per iteration are gone (same arithmetic order); on top of the phase-3 item rebalance
# baseline (speedup 1.0000x reference)
.LBB0_66:
	s_or_b64 exec, exec, s[8:9]
	v_and_b32_e32 v20, 7, v14
	s_load_dwordx16 s[16:31], s[0:1], 0x40
	v_cmp_gt_u32_e32 vcc, 4, v20
	v_lshrrev_b32_e32 v8, 3, v12
	v_and_b32_e32 v9, 8, v8
	v_cndmask_b32_e64 v2, 0, 64, vcc
	v_or_b32_e32 v2, v2, v19
	v_lshlrev_b32_e32 v3, 2, v2
	s_waitcnt lgkmcnt(0)
	global_load_dword v11, v3, s[28:29]
	v_lshl_or_b32 v34, v2, 6, v15
	v_lshlrev_b64 v[2:3], 2, v[34:35]
	v_lshl_add_u64 v[4:5], s[26:27], 0, v[2:3]
	global_load_dword v4, v[4:5], off
	v_lshl_add_u64 v[2:3], s[24:25], 0, v[2:3]
	global_load_dword v6, v[2:3], off
	v_lshrrev_b32_e32 v5, 3, v18
	v_and_b32_e32 v2, 7, v86
	v_lshlrev_b32_e32 v3, 7, v15
	v_and_b32_e32 v5, 16, v5
	v_lshl_or_b32 v8, v2, 4, v13
	v_or3_b32 v2, v3, v5, v9
	v_add_u32_e32 v10, v85, v2
	v_lshrrev_b32_e32 v126, 1, v9
	v_add_u32_e32 v126, v126, v9
	v_sub_u32_e32 v126, 4, v126
	v_add_u32_e32 v10, v10, v126
	v_or_b32_e32 v7, 0xffffff00, v18
	s_mov_b64 s[38:39], 0
	s_waitcnt vmcnt(2)
	v_mul_f32_e32 v3, 0x3fb8aa3b, v11
	v_fma_f32 v5, v11, s34, -v3
	v_rndne_f32_e32 v9, v3
	v_fmac_f32_e32 v5, 0x32a5705f, v11
	v_sub_f32_e32 v3, v3, v9
	v_add_f32_e32 v3, v3, v5
	v_cvt_i32_f32_e32 v13, v9
	v_exp_f32_e32 v5, v3
	s_waitcnt vmcnt(1)
	v_cvt_f64_f32_e32 v[2:3], v4
	v_cmp_ngt_f32_e64 s[6:7], s35, v11
	v_sub_u32_e32 v9, 63, v8
	v_ldexp_f32 v4, v5, v13
	v_cndmask_b32_e64 v4, 0, v4, s[6:7]
	v_cmp_nlt_f32_e64 s[6:7], s68, v11
	s_nop 1
	v_cndmask_b32_e64 v11, v91, v4, s[6:7]
	v_cvt_f64_f32_e32 v[4:5], v11
	s_branch .LBB0_68
.LBB0_67:
	s_or_b64 exec, exec, s[6:7]
	v_cvt_f32_i32_e32 v15, v15
	v_xor_b32_e32 v14, v14, v13
	v_add_u32_e32 v7, 0x100, v7
	v_add_u32_e32 v9, -4, v9
	v_mul_f32_e32 v15, v11, v15
	s_waitcnt vmcnt(0)
	v_mul_f32_e32 v15, v6, v15
	v_mul_f32_e32 v21, 0x3fb8aa3b, v15
	v_fma_f32 v22, v15, s34, -v21
	v_rndne_f32_e32 v23, v21
	v_fmac_f32_e32 v22, 0x32a5705f, v15
	v_sub_f32_e32 v21, v21, v23
	v_add_f32_e32 v21, v21, v22
	v_cvt_i32_f32_e32 v23, v23
	v_exp_f32_e32 v21, v21
	v_cmp_ngt_f32_e64 s[6:7], s35, v15
	v_mul_f32_e32 v22, v16, v16
	v_add_u32_e32 v8, 4, v8
	v_ldexp_f32 v21, v21, v23
	v_cndmask_b32_e64 v21, 0, v21, s[6:7]
	v_cmp_nlt_f32_e64 s[6:7], s68, v15
	s_nop 1
	v_cndmask_b32_e64 v15, v91, v21, s[6:7]
	v_fmamk_f32 v21, v22, 0xb94c1982, v89
	v_fmaak_f32 v21, v22, v21, 0xbe2aaa9d
	v_mul_f32_e32 v21, v22, v21
	v_fmac_f32_e32 v16, v16, v21
	v_fmamk_f32 v21, v22, 0x37d75334, v90
	v_fmaak_f32 v21, v22, v21, 0x3d2aabf7
	v_fmaak_f32 v21, v22, v21, 0xbf000004
	v_fma_f32 v21, v22, v21, 1.0
	v_lshlrev_b32_e32 v22, 30, v17
	v_and_b32_e32 v17, 1, v17
	v_cmp_eq_u32_e64 s[6:7], 0, v17
	v_and_b32_e32 v23, 0x80000000, v22
	s_nop 0
	v_cndmask_b32_e64 v17, v21, v16, s[6:7]
	v_xor_b32_e32 v16, 0x80000000, v16
	v_xor_b32_e32 v14, v14, v17
	v_cndmask_b32_e64 v16, v16, v21, s[6:7]
	v_xor_b32_e32 v14, v14, v23
	v_bitop3_b32 v16, v16, v22, s80 bitop3:0x78
	v_cmp_class_f32_e64 s[6:7], v13, s81
	s_nop 1
	v_cndmask_b32_e64 v13, v94, v16, s[6:7]
	v_cndmask_b32_e64 v16, v94, v14, s[6:7]
	s_movk_i32 s6, 0x2ff
	v_mul_f32_e32 v14, v15, v13
	v_mul_f32_e32 v15, v15, v16
	v_cmp_lt_u32_e64 s[6:7], s6, v7
	ds_write_b32 v10, v14
	ds_write_b32 v10, v15 offset:8
	v_add_u32_e32 v10, 32, v10
	s_or_b64 s[38:39], s[6:7], s[38:39]
	s_andn2_b64 exec, exec, s[38:39]
	s_cbranch_execz .LBB0_72

.LBB0_73:
	v_add_u32_e32 v27, s6, v24
	v_add_u32_e32 v32, v26, v25
	ds_read_b128 v[28:31], v26 offset:16400
	ds_read_b128 v[72:75], v26 offset:16416
	ds_read_b128 v[76:79], v26 offset:16432
	ds_read_b128 v[102:105], v26 offset:16448
	ds_read_b128 v[110:113], v26 offset:16464
	ds_read_b128 v[114:117], v26 offset:16480
	ds_read_b128 v[118:121], v26 offset:16496
	ds_read_b128 v[122:125], v26 offset:16384
	ds_read_b64 v[32:33], v32
	ds_read_b64 v[80:81], v27
	s_waitcnt lgkmcnt(0)
	v_pk_mul_f32 v[126:127], v[80:81], v[32:33]
	v_pk_mul_f32 v[32:33], v[80:81], v[32:33] op_sel:[1,0] op_sel_hi:[0,1]
	v_pk_add_f32 v[32:33], v[32:33], v[32:33] op_sel:[0,1] op_sel_hi:[0,1]
	v_pk_add_f32 v[80:81], v[126:127], v[126:127] op_sel:[0,1] op_sel_hi:[0,1] neg_lo:[0,1] neg_hi:[0,1]
	v_pk_mul_f32 v[124:125], v[32:33], v[124:125]
	v_pk_mul_f32 v[30:31], v[32:33], v[30:31]
	v_pk_mul_f32 v[74:75], v[32:33], v[74:75]
	v_pk_mul_f32 v[78:79], v[32:33], v[78:79]
	v_pk_mul_f32 v[104:105], v[32:33], v[104:105]
	v_pk_mul_f32 v[112:113], v[32:33], v[112:113]
	v_pk_mul_f32 v[116:117], v[32:33], v[116:117]
	v_pk_mul_f32 v[120:121], v[32:33], v[120:121]
	s_add_i32 s6, s6, 8
	v_pk_fma_f32 v[124:125], v[80:81], v[122:123], v[124:125] neg_lo:[0,0,1] neg_hi:[0,0,1]
	v_pk_fma_f32 v[30:31], v[80:81], v[28:29], v[30:31] neg_lo:[0,0,1] neg_hi:[0,0,1]
	v_pk_fma_f32 v[74:75], v[80:81], v[72:73], v[74:75] neg_lo:[0,0,1] neg_hi:[0,0,1]
	v_pk_fma_f32 v[78:79], v[80:81], v[76:77], v[78:79] neg_lo:[0,0,1] neg_hi:[0,0,1]
	v_pk_fma_f32 v[104:105], v[80:81], v[102:103], v[104:105] neg_lo:[0,0,1] neg_hi:[0,0,1]
	v_pk_fma_f32 v[112:113], v[80:81], v[110:111], v[112:113] neg_lo:[0,0,1] neg_hi:[0,0,1]
	v_pk_fma_f32 v[116:117], v[80:81], v[114:115], v[116:117] neg_lo:[0,0,1] neg_hi:[0,0,1]
	v_pk_fma_f32 v[120:121], v[80:81], v[118:119], v[120:121] neg_lo:[0,0,1] neg_hi:[0,0,1]
	v_add_u32_e32 v26, 0x80, v26
	s_cmpk_eq_i32 s6, 0x200
	v_pk_add_f32 v[16:17], v[16:17], v[124:125]
	v_pk_add_f32 v[14:15], v[14:15], v[30:31]
	v_pk_add_f32 v[12:13], v[12:13], v[74:75]
	v_pk_add_f32 v[10:11], v[10:11], v[78:79]
	v_pk_add_f32 v[8:9], v[8:9], v[104:105]
	v_pk_add_f32 v[6:7], v[6:7], v[112:113]
	v_pk_add_f32 v[4:5], v[4:5], v[116:117]
	v_pk_add_f32 v[2:3], v[2:3], v[120:121]
	s_cbranch_scc0 .LBB0_73
	v_cmp_eq_u32_e32 vcc, 3, v20
	s_and_saveexec_b64 s[6:7], vcc
	s_cbranch_execz .LBB0_80
	v_mad_u32_u24 v24, v21, s82, v82
	v_add_u32_e32 v25, v87, v23
	v_mov_b32_e32 v23, 0
	s_mov_b32 s8, 0
